# attention sub-step 1: row-sum add chain moved ahead of the per-tile barrier so nothing but the loop back-edge follows the last P.V MFMA
# speedup vs baseline: 1.0010x; 1.0010x over previous
; __device__ __forceinline__ unsigned pk2(float lo, float hi) { return pg8::cvt_pk_bf16(lo, hi); }
; #define MFMA32(a, b, c) __builtin_amdgcn_mfma_f32_32x32x16_bf16((a), (b), (c), 0, 0, 0)
; __device__ __forceinline__ void attn_phase(const Args& a, int l, bool with_ctx, unsigned char* lds) {
;     ...
;                 float ps = 0.f;
; #pragma unroll
;                 for (int r = 0; r < 16; ++r) { S[r] = __builtin_amdgcn_exp2f(S[r]); ps += S[r]; }
;                 lrun += ps;
;                 u32x4 p0, p1;
;                 p0.x = pk2(S[0], S[1]); p0.y = pk2(S[2], S[3]); p0.z = pk2(S[4], S[5]); p0.w = pk2(S[6], S[7]);
;                 p1.x = pk2(S[8], S[9]); p1.y = pk2(S[10], S[11]); p1.z = pk2(S[12], S[13]); p1.w = pk2(S[14], S[15]);
;                 const bf16x8 pa0 = __builtin_bit_cast(bf16x8, p0), pa1 = __builtin_bit_cast(bf16x8, p1);
; #pragma unroll
;                 for (int j = 0; j < 4; ++j) O[j] = MFMA32(vf[2 * j], pa0, O[j]);
; #pragma unroll
;                 for (int j = 0; j < 4; ++j) O[j] = MFMA32(vf[2 * j + 1], pa1, O[j]);
;             }
;             if (t + 1 < nt) { unsigned char* kd = kdst + (cur ^ 1) * BUF; unsigned char* vd = vdst + (cur ^ 1) * BUF;
;                 *(u32x4*)kd = k0; *(u32x4*)(kd + 9216) = k1; *(u32x4*)vd = v0; *(u32x4*)(vd + 9216) = v1; }
;             __syncthreads();
.LBB0_412:
	v_exp_f32_e32 v67, v68
	v_exp_f32_e32 v68, v69
	v_exp_f32_e32 v69, v70
	v_exp_f32_e32 v70, v71
	v_exp_f32_e32 v71, v72
	v_exp_f32_e32 v72, v73
	v_exp_f32_e32 v73, v74
	v_exp_f32_e32 v74, v75
	v_cvt_pk_bf16_f32 v184, v67, v68
	v_cvt_pk_bf16_f32 v185, v69, v70
	v_cvt_pk_bf16_f32 v186, v71, v72
	v_cvt_pk_bf16_f32 v187, v73, v74
	v_exp_f32_e32 v75, v76
	v_exp_f32_e32 v76, v77
	s_waitcnt lgkmcnt(11)
	v_mfma_f32_32x32x16_bf16 v[50:65], v[136:139], v[184:187], v[50:65]
	v_exp_f32_e32 v77, v78
	v_exp_f32_e32 v78, v79
	v_exp_f32_e32 v79, v80
	v_exp_f32_e32 v80, v81
	v_exp_f32_e32 v81, v82
	v_exp_f32_e32 v82, v83
	v_cvt_pk_bf16_f32 v214, v75, v76
	s_waitcnt lgkmcnt(9)
	v_mfma_f32_32x32x16_bf16 v[34:49], v[140:143], v[184:187], v[34:49]
	v_cvt_pk_bf16_f32 v215, v77, v78
	v_cvt_pk_bf16_f32 v216, v79, v80
	v_cvt_pk_bf16_f32 v217, v81, v82
	v_add_f32_e32 v67, 0, v67
	v_add_f32_e32 v67, v68, v67
	v_add_f32_e32 v67, v69, v67
	v_add_f32_e32 v67, v70, v67
	v_add_f32_e32 v67, v71, v67
	v_add_f32_e32 v67, v72, v67
	v_add_f32_e32 v67, v73, v67
	v_add_f32_e32 v67, v74, v67
	v_add_f32_e32 v67, v75, v67
	v_add_f32_e32 v67, v76, v67
	v_add_f32_e32 v67, v77, v67
	v_add_f32_e32 v67, v78, v67
	v_add_f32_e32 v67, v79, v67
	v_add_f32_e32 v67, v80, v67
	v_add_f32_e32 v67, v81, v67
	v_add_f32_e32 v67, v82, v67
	v_add_f32_e32 v171, v171, v67
	s_andn2_b64 vcc, exec, s[10:11]
	s_waitcnt lgkmcnt(0)
	s_barrier
	v_mfma_f32_32x32x16_bf16 v[18:33], v[144:147], v[184:187], v[18:33]
	s_waitcnt lgkmcnt(5)
	v_mfma_f32_32x32x16_bf16 v[2:17], v[132:135], v[184:187], v[2:17]
	v_mfma_f32_32x32x16_bf16 v[50:65], v[116:119], v[214:217], v[50:65]
	v_mfma_f32_32x32x16_bf16 v[34:49], v[120:123], v[214:217], v[34:49]
	v_mfma_f32_32x32x16_bf16 v[18:33], v[124:127], v[214:217], v[18:33]
	s_waitcnt lgkmcnt(4)
	v_mfma_f32_32x32x16_bf16 v[2:17], v[128:131], v[214:217], v[2:17]
